# k15 + P3 row loop: next iteration's two x1 rows prefetched into spare VGPRs (v203, v224-v253, v255), per-load waits in the unpack removed
# speedup vs baseline: 1.0019x; 1.0019x over previous
; __device__ __forceinline__ void row_load(const bf16_t* xrow, int lane, f32x4 (&xv)[8]) {
;     const u32x2* xr = (const u32x2*)xrow + lane;
; #pragma unroll
;     for (int j = 0; j < 8; ++j) { const u32x2 w = xr[64 * j]; xv[j] = (f32x4){bflo(w.x), bfhi(w.x), bflo(w.y), bfhi(w.y)}; }
; }
; __global__ void __launch_bounds__(NWAVES * 64, 2) fwd_megakernel(Args args) {
;     ...
;         f32x4 gv[8], h0[8], h1[8]; load_gain(args.in[6], F.lane, gv);
;         for (int m = F.gw; m < M; m += 2 * F.NGW) {
;             const int m1 = m + F.NGW; const bool two = m1 < M;
;             row_load(X1B + (size_t)m * D, F.lane, h0);
;             if (two) row_load(X1B + (size_t)m1 * D, F.lane, h1);
;             row_finish(h0, gv, H + (size_t)m * D, F.lane);
;             if (two) row_finish(h1, gv, H + (size_t)m1 * D, F.lane);
.LBB0_195:
	s_or_b64 exec, exec, s[0:1]
	s_add_u32 s34, s62, 0x100000
	v_cndmask_b32_e64 v0, 0, 1, s[54:55]
	s_addc_u32 s35, s63, 0
	v_cmp_ne_u32_e64 s[56:57], 1, v0
	s_andn2_b64 vcc, exec, s[54:55]
	v_lshlrev_b32_e32 v128, 2, v202
	v_cmp_lt_u32_e64 s[0:1], 47, v202
	s_waitcnt lgkmcnt(0)
	s_barrier
	s_cbranch_vccnz .LBB0_207
	v_mov_b32_e32 v143, 0
	v_lshl_add_u64 v[16:17], s[20:21], 0, v[142:143]
	v_add_co_u32_e32 v28, vcc, 0x1000, v16
	global_load_dwordx4 v[0:3], v142, s[20:21]
	global_load_dwordx4 v[4:7], v142, s[20:21] offset:1024
	global_load_dwordx4 v[8:11], v142, s[20:21] offset:2048
	global_load_dwordx4 v[12:15], v142, s[20:21] offset:3072
	v_addc_co_u32_e32 v29, vcc, 0, v17, vcc
	global_load_dwordx4 v[16:19], v[28:29], off
	global_load_dwordx4 v[20:23], v[28:29], off offset:1024
	global_load_dwordx4 v[24:27], v[28:29], off offset:2048
	s_nop 0
	global_load_dwordx4 v[28:31], v[28:29], off offset:3072
	v_mbcnt_hi_u32_b32 v38, -1, v166
	v_and_b32_e32 v39, 64, v38
	v_add_u32_e32 v39, 64, v39
	v_xor_b32_e32 v40, 1, v38
	v_cmp_lt_i32_e32 vcc, v40, v39
	v_mov_b32_e32 v129, v143
	v_add_u32_e32 v36, 0xffffff40, v128
	v_mov_b32_e32 v37, 0
	v_lshl_add_u64 v[36:37], s[34:35], 0, v[36:37]
	v_cndmask_b32_e32 v40, v38, v40, vcc
	v_lshlrev_b32_e32 v129, 2, v40
	v_xor_b32_e32 v40, 2, v38
	v_cmp_lt_i32_e32 vcc, v40, v39
	v_mov_b32_e32 v141, v143
	v_lshl_add_u64 v[32:33], s[60:61], 0, v[140:141]
	v_cndmask_b32_e32 v40, v38, v40, vcc
	v_lshlrev_b32_e32 v133, 2, v40
	v_xor_b32_e32 v40, 4, v38
	v_cmp_lt_i32_e32 vcc, v40, v39
	v_lshl_add_u64 v[34:35], s[48:49], 0, v[140:141]
	v_lshl_add_u32 v148, v202, 4, 0
	v_cndmask_b32_e32 v40, v38, v40, vcc
	v_lshlrev_b32_e32 v137, 2, v40
	v_xor_b32_e32 v40, 8, v38
	v_cmp_lt_i32_e32 vcc, v40, v39
	s_lshl_b32 s8, s30, 4
	v_add_u32_e32 v149, 0xffffffd0, v202
	v_lshlrev_b32_e32 v149, 13, v149
	v_cndmask_b32_e32 v40, v38, v40, vcc
	v_lshlrev_b32_e32 v141, 2, v40
	v_xor_b32_e32 v40, 16, v38
	v_cmp_lt_i32_e32 vcc, v40, v39
	s_mov_b32 s9, 0xffff0000
	v_mov_b32_e32 v150, 0x358637bd
	v_cndmask_b32_e32 v40, v38, v40, vcc
	v_lshlrev_b32_e32 v146, 2, v40
	v_xor_b32_e32 v40, 32, v38
	v_cmp_lt_i32_e32 vcc, v40, v39
	s_mov_b32 s18, 0xf800000
	v_mov_b32_e32 v151, 0x260
	v_cndmask_b32_e32 v38, v38, v40, vcc
	v_lshlrev_b32_e32 v147, 2, v38
	s_movk_i32 s19, 0x7fff
	s_mov_b32 s12, s68
	v_mov_b32_e32 v38, v143
	v_mov_b32_e32 v39, v143
	v_mov_b32_e32 v40, v143
	v_mov_b32_e32 v41, v143
	v_mov_b32_e32 v42, v143
	v_mov_b32_e32 v43, v143
	v_mov_b32_e32 v44, v143
	v_mov_b32_e32 v45, v143
	v_mov_b32_e32 v46, v143
	v_mov_b32_e32 v47, v143
	v_mov_b32_e32 v48, v143
	v_mov_b32_e32 v49, v143
	v_mov_b32_e32 v50, v143
	v_mov_b32_e32 v51, v143
	v_mov_b32_e32 v52, v143
	v_mov_b32_e32 v53, v143
	v_mov_b32_e32 v54, v143
	v_mov_b32_e32 v55, v143
	v_mov_b32_e32 v56, v143
	v_mov_b32_e32 v57, v143
	v_mov_b32_e32 v58, v143
	v_mov_b32_e32 v59, v143
	v_mov_b32_e32 v60, v143
	v_mov_b32_e32 v61, v143
	v_mov_b32_e32 v62, v143
	v_mov_b32_e32 v63, v143
	v_mov_b32_e32 v64, v143
	v_mov_b32_e32 v65, v143
	v_mov_b32_e32 v66, v143
	v_mov_b32_e32 v67, v143
	v_mov_b32_e32 v68, v143
	v_mov_b32_e32 v69, v143
	s_ashr_i32 s13, s12, 31
	s_lshl_b64 s[4:5], s[12:13], 12
	v_lshl_add_u64 v[38:39], v[32:33], 0, s[4:5]
	global_load_dwordx2 v[224:225], v[38:39], off
	global_load_dwordx2 v[226:227], v[38:39], off offset:512
	global_load_dwordx2 v[228:229], v[38:39], off offset:1024
	global_load_dwordx2 v[230:231], v[38:39], off offset:1536
	global_load_dwordx2 v[232:233], v[38:39], off offset:2048
	global_load_dwordx2 v[234:235], v[38:39], off offset:2560
	global_load_dwordx2 v[236:237], v[38:39], off offset:3072
	global_load_dwordx2 v[238:239], v[38:39], off offset:3584
	s_add_i32 s14, s12, s70
	s_ashr_i32 s15, s14, 31
	s_lshl_b64 s[4:5], s[14:15], 12
	v_lshl_add_u64 v[38:39], v[32:33], 0, s[4:5]
	global_load_dwordx2 v[240:241], v[38:39], off
	global_load_dwordx2 v[242:243], v[38:39], off offset:512
	global_load_dwordx2 v[244:245], v[38:39], off offset:1024
	global_load_dwordx2 v[246:247], v[38:39], off offset:1536
	global_load_dwordx2 v[248:249], v[38:39], off offset:2048
	global_load_dwordx2 v[250:251], v[38:39], off offset:2560
	global_load_dwordx2 v[252:253], v[38:39], off offset:3072
	global_load_dword v203, v[38:39], off offset:3584
	global_load_dword v255, v[38:39], off offset:3588
	s_waitcnt vmcnt(0)
	s_branch .Lp3_body_first
.LBB0_197:
	s_or_b64 exec, exec, s[6:7]
	s_add_i32 s12, s12, s8
	s_cmpk_gt_i32 s12, 0x3fff
	s_cbranch_scc1 .LBB0_207
.LBB0_198:
	s_waitcnt vmcnt(16)
.Lp3_body_first:
	s_add_i32 s14, s12, s70
	s_cmpk_lt_i32 s14, 0x4000
	s_cselect_b64 s[6:7], -1, 0
	s_ashr_i32 s13, s12, 31
	v_mov_b32_e32 v84, v224
	v_mov_b32_e32 v85, v225
	v_mov_b32_e32 v82, v226
	v_mov_b32_e32 v83, v227
	v_mov_b32_e32 v80, v228
	v_mov_b32_e32 v81, v229
	v_mov_b32_e32 v78, v230
	v_mov_b32_e32 v79, v231
	v_mov_b32_e32 v76, v232
	v_mov_b32_e32 v77, v233
	v_mov_b32_e32 v74, v234
	v_mov_b32_e32 v75, v235
	v_mov_b32_e32 v72, v236
	v_mov_b32_e32 v73, v237
	v_mov_b32_e32 v70, v238
	v_mov_b32_e32 v71, v239
	v_mov_b32_e32 v40, v240
	v_mov_b32_e32 v41, v241
	v_mov_b32_e32 v44, v242
	v_mov_b32_e32 v45, v243
	v_mov_b32_e32 v48, v244
	v_mov_b32_e32 v49, v245
	v_mov_b32_e32 v52, v246
	v_mov_b32_e32 v53, v247
	v_mov_b32_e32 v56, v248
	v_mov_b32_e32 v57, v249
	v_mov_b32_e32 v60, v250
	v_mov_b32_e32 v61, v251
	v_mov_b32_e32 v64, v252
	v_mov_b32_e32 v65, v253
	v_mov_b32_e32 v68, v203
	v_mov_b32_e32 v69, v255
	s_add_i32 s4, s12, s8
	s_cmpk_gt_i32 s4, 0x3fff
	s_cbranch_scc1 .Lp3_nopf
	s_ashr_i32 s5, s4, 31
	s_lshl_b64 s[16:17], s[4:5], 12
	v_lshl_add_u64 v[38:39], v[32:33], 0, s[16:17]
	global_load_dwordx2 v[224:225], v[38:39], off
	global_load_dwordx2 v[226:227], v[38:39], off offset:512
	global_load_dwordx2 v[228:229], v[38:39], off offset:1024
	global_load_dwordx2 v[230:231], v[38:39], off offset:1536
	global_load_dwordx2 v[232:233], v[38:39], off offset:2048
	global_load_dwordx2 v[234:235], v[38:39], off offset:2560
	global_load_dwordx2 v[236:237], v[38:39], off offset:3072
	global_load_dwordx2 v[238:239], v[38:39], off offset:3584
	s_add_i32 s4, s4, s70
	s_cmpk_gt_i32 s4, 0x3fff
	s_cbranch_scc1 .Lp3_nopf
	s_ashr_i32 s5, s4, 31
	s_lshl_b64 s[16:17], s[4:5], 12
	v_lshl_add_u64 v[38:39], v[32:33], 0, s[16:17]
	global_load_dwordx2 v[240:241], v[38:39], off
	global_load_dwordx2 v[242:243], v[38:39], off offset:512
	global_load_dwordx2 v[244:245], v[38:39], off offset:1024
	global_load_dwordx2 v[246:247], v[38:39], off offset:1536
	global_load_dwordx2 v[248:249], v[38:39], off offset:2048
	global_load_dwordx2 v[250:251], v[38:39], off offset:2560
	global_load_dwordx2 v[252:253], v[38:39], off offset:3072
	global_load_dword v203, v[38:39], off offset:3584
	global_load_dword v255, v[38:39], off offset:3588
; __device__ __forceinline__ void row_load(const bf16_t* xrow, int lane, f32x4 (&xv)[8]) {
;     const u32x2* xr = (const u32x2*)xrow + lane;
; #pragma unroll
;     for (int j = 0; j < 8; ++j) { const u32x2 w = xr[64 * j]; xv[j] = (f32x4){bflo(w.x), bfhi(w.x), bflo(w.y), bfhi(w.y)}; }
; }
; __device__ __forceinline__ void row_finish(f32x4 (&xv)[8], const f32x4 (&gv)[8], bf16_t* orow, int lane) {
;     float s = 0.f;
; #pragma unroll
;     for (int j = 0; j < 8; ++j) s += (xv[j].x * xv[j].x + xv[j].y * xv[j].y) + (xv[j].z * xv[j].z + xv[j].w * xv[j].w);
;     const float r = 1.0f / sqrtf(wave_sum(s) * (1.0f / D) + RMS_EPS);
.Lp3_nopf:
	s_nop 0
	s_lshl_b64 s[16:17], s[12:13], 11
	s_cmpk_gt_i32 s14, 0x3fff
	s_cbranch_scc1 .LBB0_200
	v_lshlrev_b32_e32 v38, 16, v40
	v_and_b32_e32 v39, 0xffff0000, v40
	v_lshlrev_b32_e32 v40, 16, v41
	v_and_b32_e32 v41, 0xffff0000, v41
	v_lshlrev_b32_e32 v42, 16, v44
	v_and_b32_e32 v43, 0xffff0000, v44
	v_lshlrev_b32_e32 v44, 16, v45
	v_and_b32_e32 v45, 0xffff0000, v45
	v_lshlrev_b32_e32 v46, 16, v48
	v_and_b32_e32 v47, 0xffff0000, v48
	v_lshlrev_b32_e32 v48, 16, v49
	v_and_b32_e32 v49, 0xffff0000, v49
	v_lshlrev_b32_e32 v50, 16, v52
	v_and_b32_e32 v51, 0xffff0000, v52
	v_lshlrev_b32_e32 v52, 16, v53
	v_and_b32_e32 v53, 0xffff0000, v53
	v_lshlrev_b32_e32 v54, 16, v56
	v_and_b32_e32 v55, 0xffff0000, v56
	v_lshlrev_b32_e32 v56, 16, v57
	v_and_b32_e32 v57, 0xffff0000, v57
	v_lshlrev_b32_e32 v58, 16, v60
	v_and_b32_e32 v59, 0xffff0000, v60
	v_lshlrev_b32_e32 v60, 16, v61
	v_and_b32_e32 v61, 0xffff0000, v61
	v_lshlrev_b32_e32 v62, 16, v64
	v_and_b32_e32 v63, 0xffff0000, v64
	v_lshlrev_b32_e32 v64, 16, v65
	v_and_b32_e32 v65, 0xffff0000, v65
	v_lshlrev_b32_e32 v66, 16, v68
	v_and_b32_e32 v67, 0xffff0000, v68
	v_lshlrev_b32_e32 v68, 16, v69
	v_and_b32_e32 v69, 0xffff0000, v69
.LBB0_200:
	v_lshlrev_b32_e32 v86, 16, v84
	v_and_b32_e32 v87, 0xffff0000, v84
	v_lshlrev_b32_e32 v84, 16, v85
	v_and_b32_e32 v85, 0xffff0000, v85
	v_lshlrev_b32_e32 v89, 16, v83
	v_lshlrev_b32_e32 v88, 16, v82
	v_and_b32_e32 v83, 0xffff0000, v83
	v_and_b32_e32 v82, 0xffff0000, v82
	v_lshlrev_b32_e32 v92, 16, v74
	v_and_b32_e32 v90, 0xffff0000, v74
	v_lshlrev_b32_e32 v103, 16, v70
	v_and_b32_e32 v101, 0xffff0000, v70
	v_mul_f32_e32 v70, v85, v85
	v_mul_f32_e32 v74, v87, v87
	v_lshlrev_b32_e32 v107, 16, v78
	v_lshlrev_b32_e32 v93, 16, v75
	v_and_b32_e32 v91, 0xffff0000, v75
	v_lshlrev_b32_e32 v94, 16, v72
	v_and_b32_e32 v95, 0xffff0000, v72
	v_lshlrev_b32_e32 v96, 16, v73
	v_and_b32_e32 v97, 0xffff0000, v73
	v_lshlrev_b32_e32 v98, 16, v71
	v_and_b32_e32 v99, 0xffff0000, v71
	v_pk_fma_f32 v[70:71], v[84:85], v[84:85], v[70:71] op_sel_hi:[1,1,0]
	v_pk_mul_f32 v[72:73], v[82:83], v[82:83]
	v_pk_fma_f32 v[74:75], v[86:87], v[86:87], v[74:75] op_sel_hi:[1,1,0]
	v_and_b32_e32 v109, 0xffff0000, v78
	v_lshlrev_b32_e32 v113, 16, v77
	v_lshlrev_b32_e32 v112, 16, v76
	v_and_b32_e32 v115, 0xffff0000, v77
	v_and_b32_e32 v114, 0xffff0000, v76
	v_pk_fma_f32 v[72:73], v[88:89], v[88:89], v[72:73]
	v_mov_b32_e32 v106, v74
	v_mov_b32_e32 v76, v70
	v_mov_b32_e32 v77, v107
	v_mul_f32_e32 v78, v109, v109
	v_pk_add_f32 v[70:71], v[74:75], v[70:71]
	v_pk_mul_f32 v[74:75], v[106:107], v[76:77]
	v_pk_add_f32 v[72:73], v[72:73], v[72:73] op_sel:[0,1] op_sel_hi:[1,0]
	v_lshlrev_b32_e32 v104, 16, v80
	v_and_b32_e32 v105, 0xffff0000, v80
	v_lshlrev_b32_e32 v80, 16, v81
	v_and_b32_e32 v81, 0xffff0000, v81
	v_mov_b32_e32 v71, v75
	v_mov_b32_e32 v73, v78
	v_lshlrev_b32_e32 v110, 16, v79
	v_and_b32_e32 v111, 0xffff0000, v79
	v_pk_add_f32 v[70:71], v[70:71], v[72:73]
	v_mul_f32_e32 v72, v105, v105
	v_mul_f32_e32 v74, v81, v81
	v_mul_f32_e32 v79, v110, v110
	v_mul_f32_e32 v100, v111, v111
	v_pk_fma_f32 v[72:73], v[104:105], v[104:105], v[72:73] op_sel_hi:[1,1,0]
	v_pk_fma_f32 v[74:75], v[80:81], v[80:81], v[74:75] op_sel_hi:[1,1,0]
	v_mov_b32_e32 v73, v79
	v_mov_b32_e32 v75, v100
	v_pk_add_f32 v[72:73], v[72:73], v[74:75]
	v_pk_mul_f32 v[74:75], v[90:91], v[90:91]
	v_pk_add_f32 v[70:71], v[70:71], v[72:73]
	v_pk_mul_f32 v[72:73], v[114:115], v[114:115]
	v_pk_add_f32 v[70:71], v[70:71], v[70:71] op_sel:[0,1] op_sel_hi:[1,0]
	v_pk_fma_f32 v[72:73], v[112:113], v[112:113], v[72:73]
	v_mov_b32_e32 v102, v70
	v_pk_add_f32 v[72:73], v[72:73], v[72:73] op_sel:[0,1] op_sel_hi:[1,0]
	v_mov_b32_e32 v77, v103
	v_mov_b32_e32 v76, v72
	v_pk_fma_f32 v[74:75], v[92:93], v[92:93], v[74:75]
	v_pk_add_f32 v[70:71], v[70:71], v[72:73]
	v_pk_mul_f32 v[72:73], v[102:103], v[76:77]
	v_mul_f32_e32 v78, v101, v101
	v_mov_b32_e32 v71, v73
	v_pk_add_f32 v[72:73], v[74:75], v[74:75] op_sel:[0,1] op_sel_hi:[1,0]
	v_mul_f32_e32 v74, v97, v97
	v_mov_b32_e32 v73, v78
	v_pk_add_f32 v[70:71], v[70:71], v[72:73]
	v_mul_f32_e32 v72, v95, v95
	v_mul_f32_e32 v79, v98, v98
	v_mul_f32_e32 v100, v99, v99
	v_pk_fma_f32 v[72:73], v[94:95], v[94:95], v[72:73] op_sel_hi:[1,1,0]
	v_pk_fma_f32 v[74:75], v[96:97], v[96:97], v[74:75] op_sel_hi:[1,1,0]
	v_mov_b32_e32 v73, v79
	v_mov_b32_e32 v75, v100
	v_pk_add_f32 v[72:73], v[72:73], v[74:75]
	v_lshl_add_u64 v[116:117], s[16:17], 1, v[34:35]
	v_pk_add_f32 v[70:71], v[70:71], v[72:73]
	v_mov_b32_e32 v108, v107
	v_add_f32_e32 v70, v70, v71
	ds_bpermute_b32 v71, v129, v70
	s_waitcnt lgkmcnt(0)
	v_add_f32_e32 v70, v70, v71
	ds_bpermute_b32 v71, v133, v70
	s_waitcnt lgkmcnt(0)
	v_add_f32_e32 v70, v70, v71
	ds_bpermute_b32 v71, v137, v70
	s_waitcnt lgkmcnt(0)
	v_add_f32_e32 v70, v70, v71
	ds_bpermute_b32 v71, v141, v70
	s_waitcnt lgkmcnt(0)
	v_add_f32_e32 v70, v70, v71
	ds_bpermute_b32 v71, v146, v70
	s_waitcnt lgkmcnt(0)
	v_add_f32_e32 v70, v70, v71
	ds_bpermute_b32 v71, v147, v70
	s_waitcnt lgkmcnt(0)
; __device__ __forceinline__ unsigned pk2(float lo, float hi) { return f2bf(lo) | (f2bf(hi) << 16); }
; __device__ __forceinline__ void row_finish(f32x4 (&xv)[8], const f32x4 (&gv)[8], bf16_t* orow, int lane) {
;     ...
;     const float r = 1.0f / sqrtf(wave_sum(s) * (1.0f / D) + RMS_EPS);
;     u32x2* o8 = (u32x2*)orow + lane;
; #pragma unroll
;     for (int j = 0; j < 8; ++j) { xv[j] = xv[j] * r * gv[j]; u32x2 w; w.x = pk2(xv[j].x, xv[j].y); w.y = pk2(xv[j].z, xv[j].w); o8[64 * j] = w; }
	v_add_f32_e32 v70, v70, v71
	v_fmamk_f32 v70, v70, 0x3a000000, v150
	v_mul_f32_e32 v71, 0x4f800000, v70
	v_cmp_gt_f32_e32 vcc, s18, v70
	s_nop 1
	v_cndmask_b32_e32 v70, v70, v71, vcc
	v_sqrt_f32_e32 v71, v70
	s_nop 0
	v_add_u32_e32 v72, -1, v71
	v_fma_f32 v73, -v72, v71, v70
	v_cmp_ge_f32_e64 s[4:5], 0, v73
	v_add_u32_e32 v73, 1, v71
	s_nop 0
	v_cndmask_b32_e64 v72, v71, v72, s[4:5]
	v_fma_f32 v71, -v73, v71, v70
	v_cmp_lt_f32_e64 s[4:5], 0, v71
	s_nop 1
	v_cndmask_b32_e64 v71, v72, v73, s[4:5]
	v_mul_f32_e32 v72, 0x37800000, v71
	v_cndmask_b32_e32 v71, v71, v72, vcc
	v_cmp_class_f32_e32 vcc, v70, v151
	s_nop 1
	v_cndmask_b32_e32 v70, v71, v70, vcc
	v_div_scale_f32 v71, s[4:5], v70, v70, 1.0
	v_rcp_f32_e32 v72, v71
	s_nop 0
	v_fma_f32 v73, -v71, v72, 1.0
	v_fmac_f32_e32 v72, v73, v72
	v_div_scale_f32 v73, vcc, 1.0, v70, 1.0
	v_mul_f32_e32 v74, v73, v72
	v_fma_f32 v75, -v71, v74, v73
	v_fmac_f32_e32 v74, v75, v72
	v_fma_f32 v71, -v71, v74, v73
	v_div_fmas_f32 v71, v71, v72, v74
	v_div_fixup_f32 v102, v71, v70, 1.0
	v_pk_mul_f32 v[72:73], v[102:103], v[86:87] op_sel_hi:[0,1]
	v_pk_mul_f32 v[72:73], v[0:1], v[72:73]
	v_pk_mul_f32 v[70:71], v[102:103], v[84:85] op_sel_hi:[0,1]
	v_bfe_u32 v74, v72, 16, 1
	v_add3_u32 v74, v72, v74, s19
	v_bfe_u32 v75, v73, 16, 1
	v_pk_mul_f32 v[70:71], v[2:3], v[70:71]
	v_lshrrev_b32_e32 v74, 16, v74
	v_add3_u32 v75, v73, v75, s19
	v_and_or_b32 v74, v75, s9, v74
	v_bfe_u32 v75, v70, 16, 1
	v_add3_u32 v75, v70, v75, s19
	v_bfe_u32 v76, v71, 16, 1
	v_lshrrev_b32_e32 v75, 16, v75
	v_add3_u32 v76, v71, v76, s19
	v_and_or_b32 v75, v76, s9, v75
	global_store_dwordx2 v[116:117], v[74:75], off
	v_mov_b32_e32 v74, v88
	v_mov_b32_e32 v75, v82
	v_pk_mul_f32 v[76:77], v[102:103], v[74:75] op_sel_hi:[0,1]
	v_pk_mul_f32 v[76:77], v[4:5], v[76:77]
	v_mov_b32_e32 v82, v89
	v_bfe_u32 v78, v76, 16, 1
	v_pk_mul_f32 v[74:75], v[102:103], v[82:83] op_sel_hi:[0,1]
	v_add3_u32 v78, v76, v78, s19
	v_bfe_u32 v79, v77, 16, 1
	v_pk_mul_f32 v[74:75], v[6:7], v[74:75]
	v_lshrrev_b32_e32 v78, 16, v78
	v_add3_u32 v79, v77, v79, s19
	v_and_or_b32 v78, v79, s9, v78
	v_bfe_u32 v79, v74, 16, 1
	v_add3_u32 v79, v74, v79, s19
	v_bfe_u32 v82, v75, 16, 1
	v_lshrrev_b32_e32 v79, 16, v79
	v_add3_u32 v82, v75, v82, s19
	v_and_or_b32 v79, v82, s9, v79
	v_pk_mul_f32 v[82:83], v[102:103], v[104:105] op_sel_hi:[0,1]
	global_store_dwordx2 v[116:117], v[78:79], off offset:512
	v_pk_mul_f32 v[78:79], v[102:103], v[80:81] op_sel_hi:[0,1]
	v_pk_mul_f32 v[80:81], v[8:9], v[82:83]
	v_pk_mul_f32 v[78:79], v[10:11], v[78:79]
	v_bfe_u32 v82, v80, 16, 1
	v_add3_u32 v82, v80, v82, s19
	v_bfe_u32 v83, v81, 16, 1
	v_lshrrev_b32_e32 v82, 16, v82
	v_add3_u32 v83, v81, v83, s19
	v_and_or_b32 v82, v83, s9, v82
	v_bfe_u32 v83, v78, 16, 1
	v_add3_u32 v83, v78, v83, s19
	v_bfe_u32 v84, v79, 16, 1
	v_lshrrev_b32_e32 v83, 16, v83
	v_add3_u32 v84, v79, v84, s19
	v_and_or_b32 v83, v84, s9, v83
	v_pk_mul_f32 v[84:85], v[108:109], v[102:103] op_sel_hi:[1,0]
	global_store_dwordx2 v[116:117], v[82:83], off offset:1024
	v_pk_mul_f32 v[84:85], v[12:13], v[84:85]
	v_pk_mul_f32 v[82:83], v[110:111], v[102:103] op_sel_hi:[1,0]
	v_bfe_u32 v86, v84, 16, 1
	v_add3_u32 v86, v84, v86, s19
	v_bfe_u32 v87, v85, 16, 1
	v_pk_mul_f32 v[82:83], v[14:15], v[82:83]
	v_lshrrev_b32_e32 v86, 16, v86
	v_add3_u32 v87, v85, v87, s19
	v_and_or_b32 v86, v87, s9, v86
	v_bfe_u32 v87, v82, 16, 1
	v_add3_u32 v87, v82, v87, s19
	v_bfe_u32 v88, v83, 16, 1
	v_lshrrev_b32_e32 v87, 16, v87
	v_add3_u32 v88, v83, v88, s19
	v_and_or_b32 v87, v88, s9, v87
	global_store_dwordx2 v[116:117], v[86:87], off offset:1536
	v_mov_b32_e32 v86, v112
	v_mov_b32_e32 v87, v114
	v_pk_mul_f32 v[88:89], v[102:103], v[86:87] op_sel_hi:[0,1]
	v_pk_mul_f32 v[88:89], v[16:17], v[88:89]
	v_mov_b32_e32 v114, v113
	v_bfe_u32 v100, v88, 16, 1
	v_pk_mul_f32 v[86:87], v[102:103], v[114:115] op_sel_hi:[0,1]
	v_add3_u32 v100, v88, v100, s19
	v_bfe_u32 v104, v89, 16, 1
	v_pk_mul_f32 v[86:87], v[18:19], v[86:87]
	v_lshrrev_b32_e32 v100, 16, v100
	v_add3_u32 v104, v89, v104, s19
	v_and_or_b32 v104, v104, s9, v100
	v_bfe_u32 v100, v86, 16, 1
	v_add3_u32 v100, v86, v100, s19
	v_bfe_u32 v105, v87, 16, 1
	v_lshrrev_b32_e32 v100, 16, v100
	v_add3_u32 v105, v87, v105, s19
	v_and_or_b32 v105, v105, s9, v100
	global_store_dwordx2 v[116:117], v[104:105], off offset:2048
	v_mov_b32_e32 v104, v92
	v_mov_b32_e32 v105, v90
	v_pk_mul_f32 v[104:105], v[102:103], v[104:105] op_sel_hi:[0,1]
	v_mov_b32_e32 v90, v93
	v_pk_mul_f32 v[92:93], v[20:21], v[104:105]
	v_pk_mul_f32 v[90:91], v[102:103], v[90:91] op_sel_hi:[0,1]
	v_bfe_u32 v100, v92, 16, 1
	v_add3_u32 v100, v92, v100, s19
	v_bfe_u32 v104, v93, 16, 1
	v_pk_mul_f32 v[90:91], v[22:23], v[90:91]
	v_lshrrev_b32_e32 v100, 16, v100
	v_add3_u32 v104, v93, v104, s19
	v_and_or_b32 v104, v104, s9, v100
	v_bfe_u32 v100, v90, 16, 1
	v_add3_u32 v100, v90, v100, s19
	v_bfe_u32 v105, v91, 16, 1
	v_lshrrev_b32_e32 v100, 16, v100
	v_add3_u32 v105, v91, v105, s19
	v_and_or_b32 v105, v105, s9, v100
	global_store_dwordx2 v[116:117], v[104:105], off offset:2560
	v_pk_mul_f32 v[104:105], v[102:103], v[94:95] op_sel_hi:[0,1]
	v_pk_mul_f32 v[94:95], v[102:103], v[96:97] op_sel_hi:[0,1]
	v_pk_mul_f32 v[96:97], v[24:25], v[104:105]
	v_pk_mul_f32 v[94:95], v[26:27], v[94:95]
	v_bfe_u32 v100, v96, 16, 1
	v_add3_u32 v100, v96, v100, s19
	v_bfe_u32 v104, v97, 16, 1
	v_lshrrev_b32_e32 v100, 16, v100
	v_add3_u32 v104, v97, v104, s19
	v_and_or_b32 v104, v104, s9, v100
	v_bfe_u32 v100, v94, 16, 1
	v_add3_u32 v100, v94, v100, s19
	v_bfe_u32 v105, v95, 16, 1
	v_lshrrev_b32_e32 v100, 16, v100
	v_add3_u32 v105, v95, v105, s19
	v_and_or_b32 v105, v105, s9, v100
	v_mov_b32_e32 v100, v103
	v_pk_mul_f32 v[100:101], v[100:101], v[102:103] op_sel_hi:[1,0]
	v_pk_mul_f32 v[98:99], v[98:99], v[102:103] op_sel_hi:[1,0]
	v_pk_mul_f32 v[100:101], v[28:29], v[100:101]
	v_pk_mul_f32 v[98:99], v[30:31], v[98:99]
	v_bfe_u32 v102, v100, 16, 1
	v_add3_u32 v102, v100, v102, s19
	v_bfe_u32 v103, v101, 16, 1
	v_lshrrev_b32_e32 v102, 16, v102
	v_add3_u32 v103, v101, v103, s19
	v_and_or_b32 v102, v103, s9, v102
	v_bfe_u32 v103, v98, 16, 1
	global_store_dwordx2 v[116:117], v[104:105], off offset:3072
	v_add3_u32 v103, v98, v103, s19
	v_bfe_u32 v104, v99, 16, 1
	v_lshrrev_b32_e32 v103, 16, v103
	v_add3_u32 v104, v99, v104, s19
	v_and_or_b32 v103, v104, s9, v103
	v_cndmask_b32_e64 v104, 0, 1, s[6:7]
	v_cmp_ne_u32_e64 s[4:5], 1, v104
	s_andn2_b64 vcc, exec, s[6:7]
	global_store_dwordx2 v[116:117], v[102:103], off offset:3584
	s_cbranch_vccnz .LBB0_202
; __device__ __forceinline__ void row_finish(f32x4 (&xv)[8], const f32x4 (&gv)[8], bf16_t* orow, int lane) {
;     float s = 0.f;
; #pragma unroll
;     for (int j = 0; j < 8; ++j) s += (xv[j].x * xv[j].x + xv[j].y * xv[j].y) + (xv[j].z * xv[j].z + xv[j].w * xv[j].w);
;     const float r = 1.0f / sqrtf(wave_sum(s) * (1.0f / D) + RMS_EPS);
	v_pk_mul_f32 v[110:111], v[40:41], v[40:41]
	v_pk_mul_f32 v[112:113], v[44:45], v[44:45]
	v_pk_mul_f32 v[114:115], v[42:43], v[42:43]
	v_pk_mul_f32 v[116:117], v[38:39], v[38:39]
	v_pk_mul_f32 v[106:107], v[48:49], v[48:49]
	v_pk_mul_f32 v[108:109], v[46:47], v[46:47]
	v_mov_b32_e32 v118, v116
	v_mov_b32_e32 v119, v114
	v_mov_b32_e32 v114, v117
	v_mov_b32_e32 v116, v110
	v_mov_b32_e32 v117, v112
	v_mov_b32_e32 v112, v111
	v_pk_add_f32 v[110:111], v[116:117], v[112:113]
	v_pk_mov_b32 v[112:113], v[108:109], v[106:107] op_sel:[1,0]
	v_mov_b32_e32 v109, v107
	v_pk_add_f32 v[106:107], v[112:113], v[108:109]
	v_pk_add_f32 v[114:115], v[118:119], v[114:115]
	v_pk_add_f32 v[106:107], v[106:107], v[106:107] op_sel_hi:[0,1]
	v_mul_f32_e32 v106, v50, v50
	v_pk_add_f32 v[110:111], v[114:115], v[110:111]
	v_pk_fma_f32 v[108:109], v[50:51], v[50:51], v[106:107] op_sel_hi:[1,1,0]
	v_mul_f32_e32 v106, v52, v52
	v_pk_add_f32 v[110:111], v[110:111], v[110:111] op_sel_hi:[0,1]
	v_pk_fma_f32 v[112:113], v[52:53], v[52:53], v[106:107] op_sel_hi:[1,1,0]
	v_mul_f32_e32 v108, v54, v54
	v_mul_f32_e32 v112, v55, v55
	v_mul_f32_e32 v106, v56, v56
	v_mul_f32_e32 v110, v57, v57
	v_pk_mul_f32 v[102:103], v[60:61], v[60:61]
	v_pk_mul_f32 v[104:105], v[58:59], v[58:59]
	v_pk_add_f32 v[108:109], v[108:109], v[112:113]
	v_pk_add_f32 v[106:107], v[106:107], v[110:111]
	v_pk_add_f32 v[106:107], v[108:109], v[106:107]
	v_pk_mov_b32 v[108:109], v[104:105], v[102:103] op_sel:[1,0]
	v_mov_b32_e32 v105, v103
	v_pk_add_f32 v[102:103], v[108:109], v[104:105]
	v_pk_add_f32 v[106:107], v[106:107], v[106:107] op_sel_hi:[0,1]
	v_pk_add_f32 v[102:103], v[102:103], v[102:103] op_sel_hi:[0,1]
	v_mul_f32_e32 v102, v62, v62
	v_pk_fma_f32 v[104:105], v[62:63], v[62:63], v[102:103] op_sel_hi:[1,1,0]
	v_mul_f32_e32 v102, v64, v64
	v_pk_fma_f32 v[108:109], v[64:65], v[64:65], v[102:103] op_sel_hi:[1,1,0]
	v_mul_f32_e32 v104, v66, v66
	v_mul_f32_e32 v108, v67, v67
	v_mul_f32_e32 v102, v68, v68
	v_mul_f32_e32 v106, v69, v69
	v_pk_add_f32 v[104:105], v[104:105], v[108:109]
	v_pk_add_f32 v[102:103], v[102:103], v[106:107]
	s_nop 0
	v_pk_add_f32 v[102:103], v[104:105], v[102:103]
	s_nop 0
	v_add_f32_e32 v102, v102, v103
	ds_bpermute_b32 v103, v129, v102
	s_waitcnt lgkmcnt(0)
	v_add_f32_e32 v102, v102, v103
	ds_bpermute_b32 v103, v133, v102
	s_waitcnt lgkmcnt(0)
	v_add_f32_e32 v102, v102, v103
	ds_bpermute_b32 v103, v137, v102
	s_waitcnt lgkmcnt(0)
	v_add_f32_e32 v102, v102, v103
	ds_bpermute_b32 v103, v141, v102
	s_waitcnt lgkmcnt(0)
	v_add_f32_e32 v102, v102, v103
	ds_bpermute_b32 v103, v146, v102
	s_waitcnt lgkmcnt(0)
	v_add_f32_e32 v102, v102, v103
	ds_bpermute_b32 v103, v147, v102
	s_waitcnt lgkmcnt(0)
; __device__ __forceinline__ unsigned pk2(float lo, float hi) { return f2bf(lo) | (f2bf(hi) << 16); }
; __device__ __forceinline__ void row_finish(f32x4 (&xv)[8], const f32x4 (&gv)[8], bf16_t* orow, int lane) {
;     ...
;     const float r = 1.0f / sqrtf(wave_sum(s) * (1.0f / D) + RMS_EPS);
;     u32x2* o8 = (u32x2*)orow + lane;
; #pragma unroll
;     for (int j = 0; j < 8; ++j) { xv[j] = xv[j] * r * gv[j]; u32x2 w; w.x = pk2(xv[j].x, xv[j].y); w.y = pk2(xv[j].z, xv[j].w); o8[64 * j] = w; }
	v_add_f32_e32 v102, v102, v103
	v_fmamk_f32 v102, v102, 0x3a000000, v150
	v_mul_f32_e32 v103, 0x4f800000, v102
	v_cmp_gt_f32_e32 vcc, s18, v102
	s_nop 1
	v_cndmask_b32_e32 v102, v102, v103, vcc
	v_sqrt_f32_e32 v103, v102
	s_nop 0
	v_add_u32_e32 v104, -1, v103
	v_fma_f32 v105, -v104, v103, v102
	v_cmp_ge_f32_e64 s[6:7], 0, v105
	v_add_u32_e32 v105, 1, v103
	s_nop 0
	v_cndmask_b32_e64 v104, v103, v104, s[6:7]
	v_fma_f32 v103, -v105, v103, v102
	v_cmp_lt_f32_e64 s[6:7], 0, v103
	s_nop 1
	v_cndmask_b32_e64 v103, v104, v105, s[6:7]
	v_mul_f32_e32 v104, 0x37800000, v103
	v_cndmask_b32_e32 v103, v103, v104, vcc
	v_cmp_class_f32_e32 vcc, v102, v151
	s_nop 1
	v_cndmask_b32_e32 v102, v103, v102, vcc
	v_div_scale_f32 v103, s[6:7], v102, v102, 1.0
	v_rcp_f32_e32 v104, v103
	s_lshl_b64 s[6:7], s[14:15], 12
	v_fma_f32 v105, -v103, v104, 1.0
	v_fmac_f32_e32 v104, v105, v104
	v_div_scale_f32 v105, vcc, 1.0, v102, 1.0
	v_mul_f32_e32 v106, v105, v104
	v_fma_f32 v107, -v103, v106, v105
	v_fmac_f32_e32 v106, v107, v104
	v_fma_f32 v103, -v103, v106, v105
	v_div_fmas_f32 v103, v103, v104, v106
	v_div_fixup_f32 v102, v103, v102, 1.0
	v_pk_mul_f32 v[38:39], v[38:39], v[102:103] op_sel_hi:[1,0]
	v_pk_mul_f32 v[40:41], v[40:41], v[102:103] op_sel_hi:[1,0]
	v_pk_mul_f32 v[38:39], v[0:1], v[38:39]
	v_pk_mul_f32 v[40:41], v[2:3], v[40:41]
	v_bfe_u32 v103, v38, 16, 1
	v_add3_u32 v103, v38, v103, s19
	v_bfe_u32 v106, v39, 16, 1
	v_lshrrev_b32_e32 v103, 16, v103
	v_add3_u32 v106, v39, v106, s19
	v_and_or_b32 v106, v106, s9, v103
	v_bfe_u32 v103, v40, 16, 1
	v_add3_u32 v103, v40, v103, s19
	v_lshrrev_b32_e32 v103, 16, v103
	v_bfe_u32 v107, v41, 16, 1
	v_pk_mul_f32 v[42:43], v[42:43], v[102:103] op_sel_hi:[1,0]
	v_add3_u32 v107, v41, v107, s19
	v_pk_mul_f32 v[42:43], v[4:5], v[42:43]
	v_lshl_add_u64 v[104:105], v[34:35], 0, s[6:7]
	v_and_or_b32 v107, v107, s9, v103
	v_pk_mul_f32 v[44:45], v[44:45], v[102:103] op_sel_hi:[1,0]
	v_bfe_u32 v103, v42, 16, 1
	global_store_dwordx2 v[104:105], v[106:107], off
	v_add3_u32 v103, v42, v103, s19
	v_bfe_u32 v106, v43, 16, 1
	v_pk_mul_f32 v[44:45], v[6:7], v[44:45]
	v_lshrrev_b32_e32 v103, 16, v103
	v_add3_u32 v106, v43, v106, s19
	v_and_or_b32 v106, v106, s9, v103
	v_bfe_u32 v103, v44, 16, 1
	v_add3_u32 v103, v44, v103, s19
	v_lshrrev_b32_e32 v103, 16, v103
	v_bfe_u32 v107, v45, 16, 1
	v_pk_mul_f32 v[46:47], v[46:47], v[102:103] op_sel_hi:[1,0]
	v_add3_u32 v107, v45, v107, s19
	v_pk_mul_f32 v[46:47], v[8:9], v[46:47]
	v_and_or_b32 v107, v107, s9, v103
	v_pk_mul_f32 v[48:49], v[48:49], v[102:103] op_sel_hi:[1,0]
	v_bfe_u32 v103, v46, 16, 1
	global_store_dwordx2 v[104:105], v[106:107], off offset:512
	v_add3_u32 v103, v46, v103, s19
	v_bfe_u32 v106, v47, 16, 1
	v_pk_mul_f32 v[48:49], v[10:11], v[48:49]
	v_lshrrev_b32_e32 v103, 16, v103
	v_add3_u32 v106, v47, v106, s19
	v_and_or_b32 v106, v106, s9, v103
	v_bfe_u32 v103, v48, 16, 1
	v_add3_u32 v103, v48, v103, s19
	v_lshrrev_b32_e32 v103, 16, v103
	v_bfe_u32 v107, v49, 16, 1
	v_pk_mul_f32 v[50:51], v[50:51], v[102:103] op_sel_hi:[1,0]
	v_add3_u32 v107, v49, v107, s19
	v_pk_mul_f32 v[50:51], v[12:13], v[50:51]
	v_and_or_b32 v107, v107, s9, v103
	v_pk_mul_f32 v[52:53], v[52:53], v[102:103] op_sel_hi:[1,0]
	v_bfe_u32 v103, v50, 16, 1
	global_store_dwordx2 v[104:105], v[106:107], off offset:1024
	v_add3_u32 v103, v50, v103, s19
	v_bfe_u32 v106, v51, 16, 1
	v_pk_mul_f32 v[52:53], v[14:15], v[52:53]
	v_lshrrev_b32_e32 v103, 16, v103
	v_add3_u32 v106, v51, v106, s19
	v_and_or_b32 v106, v106, s9, v103
	v_bfe_u32 v103, v52, 16, 1
	v_add3_u32 v103, v52, v103, s19
	v_lshrrev_b32_e32 v103, 16, v103
	v_bfe_u32 v107, v53, 16, 1
	v_pk_mul_f32 v[54:55], v[54:55], v[102:103] op_sel_hi:[1,0]
	v_add3_u32 v107, v53, v107, s19
	v_pk_mul_f32 v[54:55], v[16:17], v[54:55]
	v_and_or_b32 v107, v107, s9, v103
	v_pk_mul_f32 v[56:57], v[56:57], v[102:103] op_sel_hi:[1,0]
	v_bfe_u32 v103, v54, 16, 1
	global_store_dwordx2 v[104:105], v[106:107], off offset:1536
	v_add3_u32 v103, v54, v103, s19
	v_bfe_u32 v106, v55, 16, 1
	v_pk_mul_f32 v[56:57], v[18:19], v[56:57]
	v_lshrrev_b32_e32 v103, 16, v103
	v_add3_u32 v106, v55, v106, s19
	v_and_or_b32 v106, v106, s9, v103
	v_bfe_u32 v103, v56, 16, 1
	v_add3_u32 v103, v56, v103, s19
	v_lshrrev_b32_e32 v103, 16, v103
	v_bfe_u32 v107, v57, 16, 1
	v_pk_mul_f32 v[58:59], v[58:59], v[102:103] op_sel_hi:[1,0]
	v_add3_u32 v107, v57, v107, s19
	v_pk_mul_f32 v[58:59], v[20:21], v[58:59]
	v_and_or_b32 v107, v107, s9, v103
	v_pk_mul_f32 v[60:61], v[60:61], v[102:103] op_sel_hi:[1,0]
	v_bfe_u32 v103, v58, 16, 1
	global_store_dwordx2 v[104:105], v[106:107], off offset:2048
	v_add3_u32 v103, v58, v103, s19
	v_bfe_u32 v106, v59, 16, 1
	v_pk_mul_f32 v[60:61], v[22:23], v[60:61]
	v_lshrrev_b32_e32 v103, 16, v103
	v_add3_u32 v106, v59, v106, s19
	v_and_or_b32 v106, v106, s9, v103
	v_bfe_u32 v103, v60, 16, 1
	v_add3_u32 v103, v60, v103, s19
	v_lshrrev_b32_e32 v103, 16, v103
	v_bfe_u32 v107, v61, 16, 1
	v_pk_mul_f32 v[62:63], v[62:63], v[102:103] op_sel_hi:[1,0]
	v_add3_u32 v107, v61, v107, s19
	v_pk_mul_f32 v[62:63], v[24:25], v[62:63]
	v_and_or_b32 v107, v107, s9, v103
	v_pk_mul_f32 v[64:65], v[64:65], v[102:103] op_sel_hi:[1,0]
	v_bfe_u32 v103, v62, 16, 1
	global_store_dwordx2 v[104:105], v[106:107], off offset:2560
	v_add3_u32 v103, v62, v103, s19
	v_bfe_u32 v106, v63, 16, 1
	v_pk_mul_f32 v[64:65], v[26:27], v[64:65]
	v_lshrrev_b32_e32 v103, 16, v103
	v_add3_u32 v106, v63, v106, s19
	v_and_or_b32 v106, v106, s9, v103
	v_bfe_u32 v103, v64, 16, 1
	v_add3_u32 v103, v64, v103, s19
	v_lshrrev_b32_e32 v103, 16, v103
	v_pk_mul_f32 v[66:67], v[66:67], v[102:103] op_sel_hi:[1,0]
	v_bfe_u32 v107, v65, 16, 1
	v_pk_mul_f32 v[66:67], v[28:29], v[66:67]
	v_add3_u32 v107, v65, v107, s19
	v_pk_mul_f32 v[68:69], v[68:69], v[102:103] op_sel_hi:[1,0]
	v_bfe_u32 v102, v66, 16, 1
	v_and_or_b32 v107, v107, s9, v103
	v_add3_u32 v102, v66, v102, s19
	v_bfe_u32 v103, v67, 16, 1
	v_pk_mul_f32 v[68:69], v[30:31], v[68:69]
	v_lshrrev_b32_e32 v102, 16, v102
	v_add3_u32 v103, v67, v103, s19
	v_and_or_b32 v102, v103, s9, v102
	v_bfe_u32 v103, v68, 16, 1
	global_store_dwordx2 v[104:105], v[106:107], off offset:3072
	v_add3_u32 v103, v68, v103, s19
	v_bfe_u32 v106, v69, 16, 1
	v_lshrrev_b32_e32 v103, 16, v103
	v_add3_u32 v106, v69, v106, s19
	v_and_or_b32 v103, v106, s9, v103
	global_store_dwordx2 v[104:105], v[102:103], off offset:3584

; #define LAS __attribute__((address_space(3)))
; __global__ void __launch_bounds__(NWAVES * 64, 2) fwd_megakernel(Args args) {
;     ...
;             float mine0 = 0.f, mine1 = 0.f;
; #pragma unroll 1
;             for (int j = 0; j < 16; ++j) {
;                 float a0 = 0.f, a1 = 0.f;
; #pragma unroll
;                 for (int i = 0; i < 8; ++i) { const f32x4 w = *(const LAS f32x4*)(wz + j * D + 256 * i + 4 * F.lane);
;                     a0 += (h0[i].x * w.x + h0[i].y * w.y) + (h0[i].z * w.z + h0[i].w * w.w);
;                     a1 += (h1[i].x * w.x + h1[i].y * w.y) + (h1[i].z * w.z + h1[i].w * w.w); }
;                 a0 = wave_sum(a0); a1 = wave_sum(a1);
;                 if (F.lane == j) { mine0 = a0; mine1 = a1; }
;             }
;             if (F.lane < 16) { BZ[(size_t)m * 16 + F.lane] = mine0; if (two) BZ[(size_t)m1 * 16 + F.lane] = mine1; }
.LBB0_203:
	v_add_u32_e32 v153, s6, v148
	ds_read_b128 v[154:157], v153
	ds_read_b128 v[158:161], v153 offset:1024
	ds_read_b128 v[162:165], v153 offset:2048
	ds_read_b128 v[168:171], v153 offset:3072
	ds_read_b128 v[172:175], v153 offset:4096
	ds_read_b128 v[176:179], v153 offset:5120
	ds_read_b128 v[180:183], v153 offset:6144
	ds_read_b128 v[184:187], v153 offset:7168
	s_waitcnt lgkmcnt(7)
	v_pk_mul_f32 v[188:189], v[72:73], v[154:155]
	v_pk_mul_f32 v[190:191], v[70:71], v[156:157]
	s_waitcnt lgkmcnt(6)
	v_pk_mul_f32 v[192:193], v[76:77], v[158:159]
	v_pk_mul_f32 v[194:195], v[74:75], v[160:161]
	v_pk_fma_f32 v[154:155], v[102:103], v[154:155], v[188:189] op_sel:[0,1,0] op_sel_hi:[1,0,1]
	v_pk_fma_f32 v[156:157], v[104:105], v[156:157], v[190:191] op_sel:[0,1,0] op_sel_hi:[1,0,1]
	s_waitcnt lgkmcnt(5)
	v_pk_mul_f32 v[196:197], v[80:81], v[162:163]
	v_pk_mul_f32 v[198:199], v[78:79], v[164:165]
	v_pk_fma_f32 v[158:159], v[106:107], v[158:159], v[192:193] op_sel:[0,1,0] op_sel_hi:[1,0,1]
	v_pk_fma_f32 v[160:161], v[108:109], v[160:161], v[194:195] op_sel:[0,1,0] op_sel_hi:[1,0,1]
	v_pk_add_f32 v[154:155], v[154:155], v[156:157]
	s_waitcnt lgkmcnt(4)
	v_pk_mul_f32 v[204:205], v[84:85], v[168:169]
	v_pk_mul_f32 v[206:207], v[82:83], v[170:171]
	v_pk_fma_f32 v[162:163], v[110:111], v[162:163], v[196:197] op_sel:[0,1,0] op_sel_hi:[1,0,1]
	v_pk_fma_f32 v[164:165], v[112:113], v[164:165], v[198:199] op_sel:[0,1,0] op_sel_hi:[1,0,1]
	v_pk_add_f32 v[156:157], v[158:159], v[160:161]
	v_pk_add_f32 v[154:155], v[154:155], 0 op_sel_hi:[1,0]
	s_waitcnt lgkmcnt(3)
	v_pk_mul_f32 v[208:209], v[88:89], v[172:173]
	v_pk_mul_f32 v[210:211], v[86:87], v[174:175]
	v_pk_fma_f32 v[168:169], v[114:115], v[168:169], v[204:205] op_sel:[0,1,0] op_sel_hi:[1,0,1]
	v_pk_fma_f32 v[170:171], v[116:117], v[170:171], v[206:207] op_sel:[0,1,0] op_sel_hi:[1,0,1]
	v_pk_add_f32 v[158:159], v[162:163], v[164:165]
	v_pk_add_f32 v[154:155], v[154:155], v[156:157]
	s_waitcnt lgkmcnt(2)
	v_pk_mul_f32 v[212:213], v[92:93], v[176:177]
	v_pk_mul_f32 v[214:215], v[90:91], v[178:179]
	v_pk_fma_f32 v[172:173], v[118:119], v[172:173], v[208:209] op_sel:[0,1,0] op_sel_hi:[1,0,1]
	v_pk_fma_f32 v[174:175], v[120:121], v[174:175], v[210:211] op_sel:[0,1,0] op_sel_hi:[1,0,1]
	v_pk_add_f32 v[160:161], v[168:169], v[170:171]
	v_pk_add_f32 v[154:155], v[154:155], v[158:159]
	s_waitcnt lgkmcnt(1)
	v_pk_mul_f32 v[216:217], v[96:97], v[180:181]
	v_pk_mul_f32 v[218:219], v[94:95], v[182:183]
	v_pk_fma_f32 v[176:177], v[122:123], v[176:177], v[212:213] op_sel:[0,1,0] op_sel_hi:[1,0,1]
	v_pk_fma_f32 v[178:179], v[124:125], v[178:179], v[214:215] op_sel:[0,1,0] op_sel_hi:[1,0,1]
	v_pk_add_f32 v[162:163], v[172:173], v[174:175]
	v_pk_add_f32 v[154:155], v[154:155], v[160:161]
	s_waitcnt lgkmcnt(0)
	v_pk_mul_f32 v[220:221], v[100:101], v[184:185]
	v_pk_mul_f32 v[222:223], v[98:99], v[186:187]
	v_pk_fma_f32 v[180:181], v[126:127], v[180:181], v[216:217] op_sel:[0,1,0] op_sel_hi:[1,0,1]
	v_pk_fma_f32 v[182:183], v[130:131], v[182:183], v[218:219] op_sel:[0,1,0] op_sel_hi:[1,0,1]
	v_pk_add_f32 v[164:165], v[176:177], v[178:179]
	v_pk_add_f32 v[154:155], v[154:155], v[162:163]
	v_pk_fma_f32 v[184:185], v[134:135], v[184:185], v[220:221] op_sel:[0,1,0] op_sel_hi:[1,0,1]
	v_pk_fma_f32 v[186:187], v[144:145], v[186:187], v[222:223] op_sel:[0,1,0] op_sel_hi:[1,0,1]
	v_pk_add_f32 v[168:169], v[180:181], v[182:183]
	v_pk_add_f32 v[154:155], v[154:155], v[164:165]
	v_pk_add_f32 v[170:171], v[184:185], v[186:187]
	v_pk_add_f32 v[154:155], v[154:155], v[168:169]
	v_cmp_eq_u32_e32 vcc, s6, v149
	v_pk_add_f32 v[154:155], v[154:155], v[170:171]
	s_addk_i32 s6, 0x2000
	s_cmp_lg_u32 s6, 0x20000
	v_add_f32_dpp v154, v154, v154 quad_perm:[1,0,3,2] row_mask:0xf bank_mask:0xf
	v_add_f32_dpp v155, v155, v155 quad_perm:[1,0,3,2] row_mask:0xf bank_mask:0xf
	s_nop 0
	v_add_f32_dpp v154, v154, v154 quad_perm:[2,3,0,1] row_mask:0xf bank_mask:0xf
	v_add_f32_dpp v155, v155, v155 quad_perm:[2,3,0,1] row_mask:0xf bank_mask:0xf
	s_nop 0
	v_add_f32_dpp v154, v154, v154 row_half_mirror row_mask:0xf bank_mask:0xf
	v_add_f32_dpp v155, v155, v155 row_half_mirror row_mask:0xf bank_mask:0xf
	s_nop 0
	v_add_f32_dpp v154, v154, v154 row_mirror row_mask:0xf bank_mask:0xf
	v_add_f32_dpp v155, v155, v155 row_mirror row_mask:0xf bank_mask:0xf
	s_nop 0
	v_add_f32_dpp v154, v154, v154 row_bcast:15 row_mask:0xa bank_mask:0xf
	v_add_f32_dpp v155, v155, v155 row_bcast:15 row_mask:0xa bank_mask:0xf
	s_nop 0
	v_add_f32_dpp v154, v154, v154 row_bcast:31 row_mask:0xc bank_mask:0xf
	v_add_f32_dpp v155, v155, v155 row_bcast:31 row_mask:0xc bank_mask:0xf
	s_nop 0
	v_cndmask_b32_e32 v152, v152, v154, vcc
	v_cndmask_b32_e32 v143, v143, v155, vcc
	s_cbranch_scc1 .LBB0_203
	s_and_saveexec_b64 s[6:7], s[0:1]
	s_cbranch_execz .LBB0_197
	s_lshl_b64 s[16:17], s[12:13], 6
	v_lshl_add_u64 v[70:71], v[36:37], 0, s[16:17]
	s_and_b64 vcc, exec, s[4:5]
	global_store_dword v[70:71], v152, off
	s_cbranch_vccnz .LBB0_197
	s_lshl_b64 s[4:5], s[14:15], 6
	v_lshl_add_u64 v[70:71], v[36:37], 0, s[4:5]
	global_store_dword v[70:71], v143, off
	s_branch .LBB0_197

; __global__ void __launch_bounds__(NWAVES * 64, 2) fwd_megakernel(Args args) {
	.amdhsa_kernel _Z14fwd_megakernel4Args
		.amdhsa_group_segment_fixed_size 0
		.amdhsa_private_segment_fixed_size 0
		.amdhsa_kernarg_size 432
		.amdhsa_user_sgpr_count 2
		.amdhsa_user_sgpr_dispatch_ptr 0
		.amdhsa_user_sgpr_queue_ptr 0
		.amdhsa_user_sgpr_kernarg_segment_ptr 1
		.amdhsa_user_sgpr_dispatch_id 0
		.amdhsa_user_sgpr_kernarg_preload_length 0
		.amdhsa_user_sgpr_kernarg_preload_offset 0
		.amdhsa_user_sgpr_private_segment_size 0
		.amdhsa_uses_dynamic_stack 0
		.amdhsa_enable_private_segment 0
		.amdhsa_system_sgpr_workgroup_id_x 1
		.amdhsa_system_sgpr_workgroup_id_y 0
		.amdhsa_system_sgpr_workgroup_id_z 0
		.amdhsa_system_sgpr_workgroup_info 0
		.amdhsa_system_vgpr_workitem_id 2
		.amdhsa_next_free_vgpr 256
		.amdhsa_next_free_sgpr 98
		.amdhsa_accum_offset 256
		.amdhsa_reserve_vcc 1
		.amdhsa_float_round_mode_32 0
		.amdhsa_float_round_mode_16_64 0
		.amdhsa_float_denorm_mode_32 3
		.amdhsa_float_denorm_mode_16_64 3
		.amdhsa_dx10_clamp 1
		.amdhsa_ieee_mode 1
		.amdhsa_fp16_overflow 0
		.amdhsa_tg_split 0
		.amdhsa_exception_fp_ieee_invalid_op 0
		.amdhsa_exception_fp_denorm_src 0
		.amdhsa_exception_fp_ieee_div_zero 0
		.amdhsa_exception_fp_ieee_overflow 0
		.amdhsa_exception_fp_ieee_underflow 0
		.amdhsa_exception_fp_ieee_inexact 0
		.amdhsa_exception_int_div_zero 0
	.end_amdhsa_kernel

; __global__ void __launch_bounds__(NWAVES * 64, 2) fwd_megakernel(Args args) {
amdhsa.kernels:
  - .agpr_count:     0
    .args:
      - .offset:         0
        .size:           176
        .value_kind:     by_value
      - .offset:         176
        .size:           4
        .value_kind:     hidden_block_count_x
      - .offset:         180
        .size:           4
        .value_kind:     hidden_block_count_y
      - .offset:         184
        .size:           4
        .value_kind:     hidden_block_count_z
      - .offset:         188
        .size:           2
        .value_kind:     hidden_group_size_x
      - .offset:         190
        .size:           2
        .value_kind:     hidden_group_size_y
      - .offset:         192
        .size:           2
        .value_kind:     hidden_group_size_z
      - .offset:         194
        .size:           2
        .value_kind:     hidden_remainder_x
      - .offset:         196
        .size:           2
        .value_kind:     hidden_remainder_y
      - .offset:         198
        .size:           2
        .value_kind:     hidden_remainder_z
      - .offset:         216
        .size:           8
        .value_kind:     hidden_global_offset_x
      - .offset:         224
        .size:           8
        .value_kind:     hidden_global_offset_y
      - .offset:         232
        .size:           8
        .value_kind:     hidden_global_offset_z
      - .offset:         240
        .size:           2
        .value_kind:     hidden_grid_dims
      - .offset:         264
        .size:           8
        .value_kind:     hidden_multigrid_sync_arg
      - .offset:         296
        .size:           4
        .value_kind:     hidden_dynamic_lds_size
    .group_segment_fixed_size: 0
    .kernarg_segment_align: 8
    .kernarg_segment_size: 432
    .language:       OpenCL C
    .language_version:
      - 2
      - 0
    .max_flat_workgroup_size: 512
    .name:           _Z14fwd_megakernel4Args
    .private_segment_fixed_size: 0
    .sgpr_count:     104
    .sgpr_spill_count: 22
    .symbol:         _Z14fwd_megakernel4Args.kd
    .uniform_work_group_size: 1
    .uses_dynamic_stack: false
    .vgpr_count:     256
    .vgpr_spill_count: 0
    .wavefront_size: 64
